# barrier waiters poll the global generation word (one hop less) + P4 pipelined + residual-tile prefetch in the 4 residual GEMM epilogues
# speedup vs baseline: 1.0034x; 1.0034x over previous
; __device__ __forceinline__ unsigned xb_ld(unsigned* p)              { return __hip_atomic_load(p, __ATOMIC_RELAXED, __HIP_MEMORY_SCOPE_AGENT); }
; __device__ __forceinline__ unsigned xb_add(unsigned* p, unsigned v) { return __hip_atomic_fetch_add(p, v, __ATOMIC_RELAXED, __HIP_MEMORY_SCOPE_AGENT); }
; #define XB_SPIN(cond, bar) do { unsigned _sp = 0; while (cond) { __builtin_amdgcn_s_sleep(1); \
;     if ((++_sp & 255u) == 0u) { if (xb_ld(&(bar)[XB_TMO])) break; if (_sp > XB_SPIN_CAP) { atomicAdd(&(bar)[XB_TMO], 1u); break; } } } } while (0)
; __device__ __forceinline__ void xcd_barrier(const XcdBarrier& b) {
;     ...
;         const unsigned old = xb_add(&bar[XB_XSUB(b.x)], 1u);
;         const unsigned gen = old / nloc;
;         if (old + 1u == (gen + 1u) * nloc) {
;             __builtin_amdgcn_fence(__ATOMIC_RELEASE, "agent");
;             asm volatile("s_waitcnt vmcnt(0)" ::: "memory");
;             const unsigned og = xb_add(&bar[XB_TOP], 1u);
;             const unsigned tg = og / nx;
;             if (og + 1u == (tg + 1u) * nx) xb_add(&bar[XB_TOPGEN], 1u);
;             else XB_SPIN(xb_ld(&bar[XB_TOPGEN]) == tg, bar);
;             __builtin_amdgcn_fence(__ATOMIC_ACQUIRE, "agent");
;             xb_add(&bar[XB_XGEN(b.x)], 1u);
;             asm volatile("s_waitcnt vmcnt(0)" ::: "memory");
;         } else {
;             XB_SPIN(xb_ld(&bar[XB_XGEN(b.x)]) == gen, bar);
.LBB0_215:
	v_readlane_b32 s4, v240, 25
	s_lshl_b32 s4, s4, 8
	v_readlane_b32 s6, v240, 23
	v_readlane_b32 s7, v240, 24
	s_add_u32 s4, s6, s4
	s_addc_u32 s5, s7, 0
	v_mov_b32_e32 v3, 0x1000
	v_mov_b32_e32 v5, 1
	global_atomic_add v5, v3, v5, s[4:5] offset:1024 sc0
	v_cvt_f32_u32_e32 v3, v4
	v_sub_u32_e32 v6, 0, v4
	v_rcp_iflag_f32_e32 v3, v3
	s_nop 0
	v_mul_f32_e32 v3, 0x4f7ffffe, v3
	v_cvt_u32_f32_e32 v3, v3
	v_mul_lo_u32 v6, v6, v3
	v_mul_hi_u32 v6, v3, v6
	v_add_u32_e32 v3, v3, v6
	s_waitcnt vmcnt(0)
	v_mul_hi_u32 v3, v5, v3
	v_mul_lo_u32 v6, v3, v4
	v_sub_u32_e32 v6, v5, v6
	v_add_u32_e32 v7, 1, v3
	v_cmp_ge_u32_e32 vcc, v6, v4
	v_add_u32_e32 v5, 1, v5
	s_nop 0
	v_cndmask_b32_e32 v3, v3, v7, vcc
	v_sub_u32_e32 v7, v6, v4
	v_cndmask_b32_e32 v6, v6, v7, vcc
	v_add_u32_e32 v7, 1, v3
	v_cmp_ge_u32_e32 vcc, v6, v4
	s_nop 1
	v_cndmask_b32_e32 v3, v3, v7, vcc
	v_mul_lo_u32 v6, v4, v3
	v_add_u32_e32 v4, v6, v4
	v_cmp_ne_u32_e32 vcc, v5, v4
	s_and_saveexec_b64 s[6:7], vcc
	s_xor_b64 s[6:7], exec, s[6:7]
	s_cbranch_execz .LBB0_229
	s_waitcnt lgkmcnt(0)
	v_mov_b32_e32 v2, 0x7100
	global_load_dword v2, v2, s[30:31] offset:1024 sc1
	s_add_u32 s14, s30, 0x7500
	s_addc_u32 s15, s31, 0
	s_waitcnt vmcnt(0)
	v_cmp_eq_u32_e32 vcc, v2, v3
	s_and_saveexec_b64 s[8:9], vcc
	s_cbranch_execz .LBB0_228
	s_add_u32 s12, s30, 0x4200
	s_addc_u32 s13, s31, 0
	s_mov_b32 s10, 1
	s_mov_b64 s[16:17], 0
	v_mov_b32_e32 v2, 0
	s_branch .LBB0_219

; __device__ __forceinline__ unsigned xb_ld(unsigned* p)              { return __hip_atomic_load(p, __ATOMIC_RELAXED, __HIP_MEMORY_SCOPE_AGENT); }
; __device__ __forceinline__ unsigned xb_add(unsigned* p, unsigned v) { return __hip_atomic_fetch_add(p, v, __ATOMIC_RELAXED, __HIP_MEMORY_SCOPE_AGENT); }
; #define XB_SPIN(cond, bar) do { unsigned _sp = 0; while (cond) { __builtin_amdgcn_s_sleep(1); \
;     if ((++_sp & 255u) == 0u) { if (xb_ld(&(bar)[XB_TMO])) break; if (_sp > XB_SPIN_CAP) { atomicAdd(&(bar)[XB_TMO], 1u); break; } } } } while (0)
; __device__ __forceinline__ void xcd_barrier(const XcdBarrier& b) {
;     ...
;         const unsigned old = xb_add(&bar[XB_XSUB(b.x)], 1u);
;         const unsigned gen = old / nloc;
;         if (old + 1u == (gen + 1u) * nloc) {
;             __builtin_amdgcn_fence(__ATOMIC_RELEASE, "agent");
;             asm volatile("s_waitcnt vmcnt(0)" ::: "memory");
;             const unsigned og = xb_add(&bar[XB_TOP], 1u);
;             const unsigned tg = og / nx;
;             if (og + 1u == (tg + 1u) * nx) xb_add(&bar[XB_TOPGEN], 1u);
;             else XB_SPIN(xb_ld(&bar[XB_TOPGEN]) == tg, bar);
;             __builtin_amdgcn_fence(__ATOMIC_ACQUIRE, "agent");
;             xb_add(&bar[XB_XGEN(b.x)], 1u);
;             asm volatile("s_waitcnt vmcnt(0)" ::: "memory");
;         } else {
;             XB_SPIN(xb_ld(&bar[XB_XGEN(b.x)]) == gen, bar);
.LBB0_539:
	v_readlane_b32 s4, v240, 25
	s_lshl_b32 s4, s4, 8
	v_readlane_b32 s6, v240, 23
	v_readlane_b32 s7, v240, 24
	s_add_u32 s4, s6, s4
	s_addc_u32 s5, s7, 0
	v_mov_b32_e32 v3, 0x1000
	v_mov_b32_e32 v5, 1
	global_atomic_add v5, v3, v5, s[4:5] offset:1024 sc0
	v_cvt_f32_u32_e32 v3, v4
	v_sub_u32_e32 v6, 0, v4
	v_rcp_iflag_f32_e32 v3, v3
	s_nop 0
	v_mul_f32_e32 v3, 0x4f7ffffe, v3
	v_cvt_u32_f32_e32 v3, v3
	v_mul_lo_u32 v6, v6, v3
	v_mul_hi_u32 v6, v3, v6
	v_add_u32_e32 v3, v3, v6
	s_waitcnt vmcnt(0)
	v_mul_hi_u32 v3, v5, v3
	v_mul_lo_u32 v6, v3, v4
	v_sub_u32_e32 v6, v5, v6
	v_add_u32_e32 v7, 1, v3
	v_cmp_ge_u32_e32 vcc, v6, v4
	v_add_u32_e32 v5, 1, v5
	s_nop 0
	v_cndmask_b32_e32 v3, v3, v7, vcc
	v_sub_u32_e32 v7, v6, v4
	v_cndmask_b32_e32 v6, v6, v7, vcc
	v_add_u32_e32 v7, 1, v3
	v_cmp_ge_u32_e32 vcc, v6, v4
	s_nop 1
	v_cndmask_b32_e32 v3, v3, v7, vcc
	v_mul_lo_u32 v6, v4, v3
	v_add_u32_e32 v4, v6, v4
	v_cmp_ne_u32_e32 vcc, v5, v4
	s_and_saveexec_b64 s[6:7], vcc
	s_xor_b64 s[6:7], exec, s[6:7]
	s_cbranch_execz .LBB0_553
	s_waitcnt lgkmcnt(0)
	v_mov_b32_e32 v2, 0x7100
	global_load_dword v2, v2, s[30:31] offset:1024 sc1
	s_add_u32 s16, s30, 0x7500
	s_addc_u32 s17, s31, 0
	s_waitcnt vmcnt(0)
	v_cmp_eq_u32_e32 vcc, v2, v3
	s_and_saveexec_b64 s[8:9], vcc
	s_cbranch_execz .LBB0_552
	s_add_u32 s14, s30, 0x4200
	s_addc_u32 s15, s31, 0
	s_mov_b32 s10, 1
	s_mov_b64 s[18:19], 0
	v_mov_b32_e32 v2, 0
	s_branch .LBB0_543

; __device__ __forceinline__ unsigned xb_ld(unsigned* p)              { return __hip_atomic_load(p, __ATOMIC_RELAXED, __HIP_MEMORY_SCOPE_AGENT); }
; __device__ __forceinline__ unsigned xb_add(unsigned* p, unsigned v) { return __hip_atomic_fetch_add(p, v, __ATOMIC_RELAXED, __HIP_MEMORY_SCOPE_AGENT); }
; #define XB_SPIN(cond, bar) do { unsigned _sp = 0; while (cond) { __builtin_amdgcn_s_sleep(1); \
;     if ((++_sp & 255u) == 0u) { if (xb_ld(&(bar)[XB_TMO])) break; if (_sp > XB_SPIN_CAP) { atomicAdd(&(bar)[XB_TMO], 1u); break; } } } } while (0)
; __device__ __forceinline__ void xcd_barrier(const XcdBarrier& b) {
;     ...
;         const unsigned old = xb_add(&bar[XB_XSUB(b.x)], 1u);
;         const unsigned gen = old / nloc;
;         if (old + 1u == (gen + 1u) * nloc) {
;             __builtin_amdgcn_fence(__ATOMIC_RELEASE, "agent");
;             asm volatile("s_waitcnt vmcnt(0)" ::: "memory");
;             const unsigned og = xb_add(&bar[XB_TOP], 1u);
;             const unsigned tg = og / nx;
;             if (og + 1u == (tg + 1u) * nx) xb_add(&bar[XB_TOPGEN], 1u);
;             else XB_SPIN(xb_ld(&bar[XB_TOPGEN]) == tg, bar);
;             __builtin_amdgcn_fence(__ATOMIC_ACQUIRE, "agent");
;             xb_add(&bar[XB_XGEN(b.x)], 1u);
;             asm volatile("s_waitcnt vmcnt(0)" ::: "memory");
;         } else {
;             XB_SPIN(xb_ld(&bar[XB_XGEN(b.x)]) == gen, bar);
.LBB0_696:
	v_readlane_b32 s4, v240, 25
	s_lshl_b32 s4, s4, 8
	v_readlane_b32 s6, v240, 23
	v_readlane_b32 s7, v240, 24
	s_add_u32 s4, s6, s4
	s_addc_u32 s5, s7, 0
	v_mov_b32_e32 v2, 0x1000
	v_mov_b32_e32 v4, 1
	global_atomic_add v4, v2, v4, s[4:5] offset:1024 sc0
	v_cvt_f32_u32_e32 v2, v3
	v_sub_u32_e32 v5, 0, v3
	v_rcp_iflag_f32_e32 v2, v2
	s_nop 0
	v_mul_f32_e32 v2, 0x4f7ffffe, v2
	v_cvt_u32_f32_e32 v2, v2
	v_mul_lo_u32 v5, v5, v2
	v_mul_hi_u32 v5, v2, v5
	v_add_u32_e32 v2, v2, v5
	s_waitcnt vmcnt(0)
	v_mul_hi_u32 v2, v4, v2
	v_mul_lo_u32 v5, v2, v3
	v_sub_u32_e32 v5, v4, v5
	v_add_u32_e32 v6, 1, v2
	v_cmp_ge_u32_e32 vcc, v5, v3
	v_add_u32_e32 v4, 1, v4
	s_nop 0
	v_cndmask_b32_e32 v2, v2, v6, vcc
	v_sub_u32_e32 v6, v5, v3
	v_cndmask_b32_e32 v5, v5, v6, vcc
	v_add_u32_e32 v6, 1, v2
	v_cmp_ge_u32_e32 vcc, v5, v3
	s_nop 1
	v_cndmask_b32_e32 v2, v2, v6, vcc
	v_mul_lo_u32 v5, v3, v2
	v_add_u32_e32 v3, v5, v3
	v_cmp_ne_u32_e32 vcc, v4, v3
	s_and_saveexec_b64 s[6:7], vcc
	s_xor_b64 s[6:7], exec, s[6:7]
	s_cbranch_execz .LBB0_710
	s_waitcnt lgkmcnt(0)
	v_mov_b32_e32 v1, 0x7100
	global_load_dword v1, v1, s[30:31] offset:1024 sc1
	s_add_u32 s16, s30, 0x7500
	s_addc_u32 s17, s31, 0
	s_waitcnt vmcnt(0)
	v_cmp_eq_u32_e32 vcc, v1, v2
	s_and_saveexec_b64 s[8:9], vcc
	s_cbranch_execz .LBB0_709
	s_add_u32 s14, s30, 0x4200
	s_addc_u32 s15, s31, 0
	s_mov_b32 s10, 1
	s_mov_b64 s[18:19], 0
	v_mov_b32_e32 v1, 0
	s_branch .LBB0_700

; __device__ __forceinline__ unsigned xb_ld(unsigned* p)              { return __hip_atomic_load(p, __ATOMIC_RELAXED, __HIP_MEMORY_SCOPE_AGENT); }
; __device__ __forceinline__ unsigned xb_add(unsigned* p, unsigned v) { return __hip_atomic_fetch_add(p, v, __ATOMIC_RELAXED, __HIP_MEMORY_SCOPE_AGENT); }
; #define XB_SPIN(cond, bar) do { unsigned _sp = 0; while (cond) { __builtin_amdgcn_s_sleep(1); \
;     if ((++_sp & 255u) == 0u) { if (xb_ld(&(bar)[XB_TMO])) break; if (_sp > XB_SPIN_CAP) { atomicAdd(&(bar)[XB_TMO], 1u); break; } } } } while (0)
; __device__ __forceinline__ void xcd_barrier(const XcdBarrier& b) {
;     ...
;         const unsigned old = xb_add(&bar[XB_XSUB(b.x)], 1u);
;         const unsigned gen = old / nloc;
;         if (old + 1u == (gen + 1u) * nloc) {
;             __builtin_amdgcn_fence(__ATOMIC_RELEASE, "agent");
;             asm volatile("s_waitcnt vmcnt(0)" ::: "memory");
;             const unsigned og = xb_add(&bar[XB_TOP], 1u);
;             const unsigned tg = og / nx;
;             if (og + 1u == (tg + 1u) * nx) xb_add(&bar[XB_TOPGEN], 1u);
;             else XB_SPIN(xb_ld(&bar[XB_TOPGEN]) == tg, bar);
;             __builtin_amdgcn_fence(__ATOMIC_ACQUIRE, "agent");
;             xb_add(&bar[XB_XGEN(b.x)], 1u);
;             asm volatile("s_waitcnt vmcnt(0)" ::: "memory");
;         } else {
;             XB_SPIN(xb_ld(&bar[XB_XGEN(b.x)]) == gen, bar);
.LBB0_832:
	v_readlane_b32 s4, v240, 25
	s_lshl_b32 s4, s4, 8
	v_readlane_b32 s14, v240, 23
	v_readlane_b32 s15, v240, 24
	s_add_u32 s4, s14, s4
	s_addc_u32 s5, s15, 0
	v_mov_b32_e32 v2, 0x1000
	v_mov_b32_e32 v4, 1
	global_atomic_add v4, v2, v4, s[4:5] offset:1024 sc0
	v_cvt_f32_u32_e32 v2, v3
	v_sub_u32_e32 v5, 0, v3
	v_rcp_iflag_f32_e32 v2, v2
	s_nop 0
	v_mul_f32_e32 v2, 0x4f7ffffe, v2
	v_cvt_u32_f32_e32 v2, v2
	v_mul_lo_u32 v5, v5, v2
	v_mul_hi_u32 v5, v2, v5
	v_add_u32_e32 v2, v2, v5
	s_waitcnt vmcnt(0)
	v_mul_hi_u32 v2, v4, v2
	v_mul_lo_u32 v5, v2, v3
	v_sub_u32_e32 v5, v4, v5
	v_add_u32_e32 v6, 1, v2
	v_cmp_ge_u32_e32 vcc, v5, v3
	v_add_u32_e32 v4, 1, v4
	s_nop 0
	v_cndmask_b32_e32 v2, v2, v6, vcc
	v_sub_u32_e32 v6, v5, v3
	v_cndmask_b32_e32 v5, v5, v6, vcc
	v_add_u32_e32 v6, 1, v2
	v_cmp_ge_u32_e32 vcc, v5, v3
	s_nop 1
	v_cndmask_b32_e32 v2, v2, v6, vcc
	v_mul_lo_u32 v5, v3, v2
	v_add_u32_e32 v3, v5, v3
	v_cmp_ne_u32_e32 vcc, v4, v3
	s_and_saveexec_b64 s[14:15], vcc
	s_xor_b64 s[14:15], exec, s[14:15]
	s_cbranch_execz .LBB0_846
	s_waitcnt lgkmcnt(0)
	v_mov_b32_e32 v1, 0x7100
	global_load_dword v1, v1, s[30:31] offset:1024 sc1
	s_add_u32 s20, s30, 0x7500
	s_addc_u32 s21, s31, 0
	s_waitcnt vmcnt(0)
	v_cmp_eq_u32_e32 vcc, v1, v2
	s_and_saveexec_b64 s[16:17], vcc
	s_cbranch_execz .LBB0_845
	s_add_u32 s18, s30, 0x4200
	s_addc_u32 s19, s31, 0
	s_mov_b32 s10, 1
	s_mov_b64 s[22:23], 0
	v_mov_b32_e32 v1, 0
	s_branch .LBB0_836

; __device__ __forceinline__ unsigned xb_ld(unsigned* p)              { return __hip_atomic_load(p, __ATOMIC_RELAXED, __HIP_MEMORY_SCOPE_AGENT); }
; __device__ __forceinline__ unsigned xb_add(unsigned* p, unsigned v) { return __hip_atomic_fetch_add(p, v, __ATOMIC_RELAXED, __HIP_MEMORY_SCOPE_AGENT); }
; #define XB_SPIN(cond, bar) do { unsigned _sp = 0; while (cond) { __builtin_amdgcn_s_sleep(1); \
;     if ((++_sp & 255u) == 0u) { if (xb_ld(&(bar)[XB_TMO])) break; if (_sp > XB_SPIN_CAP) { atomicAdd(&(bar)[XB_TMO], 1u); break; } } } } while (0)
; __device__ __forceinline__ void xcd_barrier(const XcdBarrier& b) {
;     ...
;         const unsigned old = xb_add(&bar[XB_XSUB(b.x)], 1u);
;         const unsigned gen = old / nloc;
;         if (old + 1u == (gen + 1u) * nloc) {
;             __builtin_amdgcn_fence(__ATOMIC_RELEASE, "agent");
;             asm volatile("s_waitcnt vmcnt(0)" ::: "memory");
;             const unsigned og = xb_add(&bar[XB_TOP], 1u);
;             const unsigned tg = og / nx;
;             if (og + 1u == (tg + 1u) * nx) xb_add(&bar[XB_TOPGEN], 1u);
;             else XB_SPIN(xb_ld(&bar[XB_TOPGEN]) == tg, bar);
;             __builtin_amdgcn_fence(__ATOMIC_ACQUIRE, "agent");
;             xb_add(&bar[XB_XGEN(b.x)], 1u);
;             asm volatile("s_waitcnt vmcnt(0)" ::: "memory");
;         } else {
;             XB_SPIN(xb_ld(&bar[XB_XGEN(b.x)]) == gen, bar);
.LBB0_894:
	v_readlane_b32 s4, v240, 25
	s_lshl_b32 s4, s4, 8
	v_readlane_b32 s10, v240, 23
	v_readlane_b32 s11, v240, 24
	s_add_u32 s4, s10, s4
	s_addc_u32 s5, s11, 0
	v_mov_b32_e32 v2, 0x1000
	v_mov_b32_e32 v4, 1
	global_atomic_add v4, v2, v4, s[4:5] offset:1024 sc0
	v_cvt_f32_u32_e32 v2, v3
	v_sub_u32_e32 v5, 0, v3
	v_rcp_iflag_f32_e32 v2, v2
	s_nop 0
	v_mul_f32_e32 v2, 0x4f7ffffe, v2
	v_cvt_u32_f32_e32 v2, v2
	v_mul_lo_u32 v5, v5, v2
	v_mul_hi_u32 v5, v2, v5
	v_add_u32_e32 v2, v2, v5
	s_waitcnt vmcnt(0)
	v_mul_hi_u32 v2, v4, v2
	v_mul_lo_u32 v5, v2, v3
	v_sub_u32_e32 v5, v4, v5
	v_add_u32_e32 v6, 1, v2
	v_cmp_ge_u32_e32 vcc, v5, v3
	v_add_u32_e32 v4, 1, v4
	s_nop 0
	v_cndmask_b32_e32 v2, v2, v6, vcc
	v_sub_u32_e32 v6, v5, v3
	v_cndmask_b32_e32 v5, v5, v6, vcc
	v_add_u32_e32 v6, 1, v2
	v_cmp_ge_u32_e32 vcc, v5, v3
	s_nop 1
	v_cndmask_b32_e32 v2, v2, v6, vcc
	v_mul_lo_u32 v5, v3, v2
	v_add_u32_e32 v3, v5, v3
	v_cmp_ne_u32_e32 vcc, v4, v3
	s_and_saveexec_b64 s[10:11], vcc
	s_xor_b64 s[14:15], exec, s[10:11]
	s_cbranch_execz .LBB0_908
	s_waitcnt lgkmcnt(0)
	v_mov_b32_e32 v1, 0x7100
	global_load_dword v1, v1, s[30:31] offset:1024 sc1
	s_add_u32 s20, s30, 0x7500
	s_addc_u32 s21, s31, 0
	s_waitcnt vmcnt(0)
	v_cmp_eq_u32_e32 vcc, v1, v2
	s_and_saveexec_b64 s[16:17], vcc
	s_cbranch_execz .LBB0_907
	s_add_u32 s18, s30, 0x4200
	s_addc_u32 s19, s31, 0
	s_mov_b32 s10, 1
	s_mov_b64 s[22:23], 0
	v_mov_b32_e32 v1, 0
	s_branch .LBB0_898

; __device__ __forceinline__ unsigned xb_ld(unsigned* p)              { return __hip_atomic_load(p, __ATOMIC_RELAXED, __HIP_MEMORY_SCOPE_AGENT); }
; __device__ __forceinline__ unsigned xb_add(unsigned* p, unsigned v) { return __hip_atomic_fetch_add(p, v, __ATOMIC_RELAXED, __HIP_MEMORY_SCOPE_AGENT); }
; #define XB_SPIN(cond, bar) do { unsigned _sp = 0; while (cond) { __builtin_amdgcn_s_sleep(1); \
;     if ((++_sp & 255u) == 0u) { if (xb_ld(&(bar)[XB_TMO])) break; if (_sp > XB_SPIN_CAP) { atomicAdd(&(bar)[XB_TMO], 1u); break; } } } } while (0)
; __device__ __forceinline__ void xcd_barrier(const XcdBarrier& b) {
;     ...
;         const unsigned old = xb_add(&bar[XB_XSUB(b.x)], 1u);
;         const unsigned gen = old / nloc;
;         if (old + 1u == (gen + 1u) * nloc) {
;             __builtin_amdgcn_fence(__ATOMIC_RELEASE, "agent");
;             asm volatile("s_waitcnt vmcnt(0)" ::: "memory");
;             const unsigned og = xb_add(&bar[XB_TOP], 1u);
;             const unsigned tg = og / nx;
;             if (og + 1u == (tg + 1u) * nx) xb_add(&bar[XB_TOPGEN], 1u);
;             else XB_SPIN(xb_ld(&bar[XB_TOPGEN]) == tg, bar);
;             __builtin_amdgcn_fence(__ATOMIC_ACQUIRE, "agent");
;             xb_add(&bar[XB_XGEN(b.x)], 1u);
;             asm volatile("s_waitcnt vmcnt(0)" ::: "memory");
;         } else {
;             XB_SPIN(xb_ld(&bar[XB_XGEN(b.x)]) == gen, bar);
.LBB0_1181:
	v_readlane_b32 s4, v240, 25
	s_lshl_b32 s4, s4, 8
	v_readlane_b32 s10, v240, 23
	v_readlane_b32 s11, v240, 24
	s_add_u32 s4, s10, s4
	s_addc_u32 s5, s11, 0
	v_mov_b32_e32 v2, 0x1000
	v_mov_b32_e32 v4, 1
	global_atomic_add v4, v2, v4, s[4:5] offset:1024 sc0
	v_cvt_f32_u32_e32 v2, v3
	v_sub_u32_e32 v5, 0, v3
	v_rcp_iflag_f32_e32 v2, v2
	s_nop 0
	v_mul_f32_e32 v2, 0x4f7ffffe, v2
	v_cvt_u32_f32_e32 v2, v2
	v_mul_lo_u32 v5, v5, v2
	v_mul_hi_u32 v5, v2, v5
	v_add_u32_e32 v2, v2, v5
	s_waitcnt vmcnt(0)
	v_mul_hi_u32 v2, v4, v2
	v_mul_lo_u32 v5, v2, v3
	v_sub_u32_e32 v5, v4, v5
	v_add_u32_e32 v6, 1, v2
	v_cmp_ge_u32_e32 vcc, v5, v3
	v_add_u32_e32 v4, 1, v4
	s_nop 0
	v_cndmask_b32_e32 v2, v2, v6, vcc
	v_sub_u32_e32 v6, v5, v3
	v_cndmask_b32_e32 v5, v5, v6, vcc
	v_add_u32_e32 v6, 1, v2
	v_cmp_ge_u32_e32 vcc, v5, v3
	s_nop 1
	v_cndmask_b32_e32 v2, v2, v6, vcc
	v_mul_lo_u32 v5, v3, v2
	v_add_u32_e32 v3, v5, v3
	v_cmp_ne_u32_e32 vcc, v4, v3
	s_and_saveexec_b64 s[10:11], vcc
	s_xor_b64 s[16:17], exec, s[10:11]
	s_cbranch_execz .LBB0_1195
	s_waitcnt lgkmcnt(0)
	v_mov_b32_e32 v1, 0x7100
	global_load_dword v1, v1, s[30:31] offset:1024 sc1
	s_add_u32 s22, s30, 0x7500
	s_addc_u32 s23, s31, 0
	s_waitcnt vmcnt(0)
	v_cmp_eq_u32_e32 vcc, v1, v2
	s_and_saveexec_b64 s[18:19], vcc
	s_cbranch_execz .LBB0_1194
	s_add_u32 s20, s30, 0x4200
	s_addc_u32 s21, s31, 0
	s_mov_b32 s10, 1
	s_mov_b64 s[36:37], 0
	v_mov_b32_e32 v1, 0
	s_branch .LBB0_1185

; __device__ __forceinline__ unsigned xb_ld(unsigned* p)              { return __hip_atomic_load(p, __ATOMIC_RELAXED, __HIP_MEMORY_SCOPE_AGENT); }
; __device__ __forceinline__ unsigned xb_add(unsigned* p, unsigned v) { return __hip_atomic_fetch_add(p, v, __ATOMIC_RELAXED, __HIP_MEMORY_SCOPE_AGENT); }
; #define XB_SPIN(cond, bar) do { unsigned _sp = 0; while (cond) { __builtin_amdgcn_s_sleep(1); \
;     if ((++_sp & 255u) == 0u) { if (xb_ld(&(bar)[XB_TMO])) break; if (_sp > XB_SPIN_CAP) { atomicAdd(&(bar)[XB_TMO], 1u); break; } } } } while (0)
; __device__ __forceinline__ void xcd_barrier(const XcdBarrier& b) {
;     ...
;         const unsigned old = xb_add(&bar[XB_XSUB(b.x)], 1u);
;         const unsigned gen = old / nloc;
;         if (old + 1u == (gen + 1u) * nloc) {
;             __builtin_amdgcn_fence(__ATOMIC_RELEASE, "agent");
;             asm volatile("s_waitcnt vmcnt(0)" ::: "memory");
;             const unsigned og = xb_add(&bar[XB_TOP], 1u);
;             const unsigned tg = og / nx;
;             if (og + 1u == (tg + 1u) * nx) xb_add(&bar[XB_TOPGEN], 1u);
;             else XB_SPIN(xb_ld(&bar[XB_TOPGEN]) == tg, bar);
;             __builtin_amdgcn_fence(__ATOMIC_ACQUIRE, "agent");
;             xb_add(&bar[XB_XGEN(b.x)], 1u);
;             asm volatile("s_waitcnt vmcnt(0)" ::: "memory");
;         } else {
;             XB_SPIN(xb_ld(&bar[XB_XGEN(b.x)]) == gen, bar);
.LBB0_1954:
	v_readlane_b32 s4, v240, 25
	s_lshl_b32 s4, s4, 8
	v_readlane_b32 s10, v240, 23
	v_readlane_b32 s11, v240, 24
	s_add_u32 s4, s10, s4
	s_addc_u32 s5, s11, 0
	v_mov_b32_e32 v2, 0x1000
	v_mov_b32_e32 v4, 1
	global_atomic_add v4, v2, v4, s[4:5] offset:1024 sc0
	v_cvt_f32_u32_e32 v2, v3
	v_sub_u32_e32 v5, 0, v3
	v_rcp_iflag_f32_e32 v2, v2
	s_nop 0
	v_mul_f32_e32 v2, 0x4f7ffffe, v2
	v_cvt_u32_f32_e32 v2, v2
	v_mul_lo_u32 v5, v5, v2
	v_mul_hi_u32 v5, v2, v5
	v_add_u32_e32 v2, v2, v5
	s_waitcnt vmcnt(0)
	v_mul_hi_u32 v2, v4, v2
	v_mul_lo_u32 v5, v2, v3
	v_sub_u32_e32 v5, v4, v5
	v_add_u32_e32 v6, 1, v2
	v_cmp_ge_u32_e32 vcc, v5, v3
	v_add_u32_e32 v4, 1, v4
	s_nop 0
	v_cndmask_b32_e32 v2, v2, v6, vcc
	v_sub_u32_e32 v6, v5, v3
	v_cndmask_b32_e32 v5, v5, v6, vcc
	v_add_u32_e32 v6, 1, v2
	v_cmp_ge_u32_e32 vcc, v5, v3
	s_nop 1
	v_cndmask_b32_e32 v2, v2, v6, vcc
	v_mul_lo_u32 v5, v3, v2
	v_add_u32_e32 v3, v5, v3
	v_cmp_ne_u32_e32 vcc, v4, v3
	s_and_saveexec_b64 s[10:11], vcc
	s_xor_b64 s[12:13], exec, s[10:11]
	s_cbranch_execz .LBB0_1968
	s_waitcnt lgkmcnt(0)
	v_mov_b32_e32 v1, 0x7100
	global_load_dword v1, v1, s[30:31] offset:1024 sc1
	s_add_u32 s20, s30, 0x7500
	s_addc_u32 s21, s31, 0
	s_waitcnt vmcnt(0)
	v_cmp_eq_u32_e32 vcc, v1, v2
	s_and_saveexec_b64 s[16:17], vcc
	s_cbranch_execz .LBB0_1967
	s_add_u32 s18, s30, 0x4200
	s_addc_u32 s19, s31, 0
	s_mov_b32 s10, 1
	s_mov_b64 s[22:23], 0
	v_mov_b32_e32 v1, 0
	s_branch .LBB0_1958

; __device__ __forceinline__ unsigned xb_ld(unsigned* p)              { return __hip_atomic_load(p, __ATOMIC_RELAXED, __HIP_MEMORY_SCOPE_AGENT); }
; __device__ __forceinline__ unsigned xb_add(unsigned* p, unsigned v) { return __hip_atomic_fetch_add(p, v, __ATOMIC_RELAXED, __HIP_MEMORY_SCOPE_AGENT); }
; #define XB_SPIN(cond, bar) do { unsigned _sp = 0; while (cond) { __builtin_amdgcn_s_sleep(1); \
;     if ((++_sp & 255u) == 0u) { if (xb_ld(&(bar)[XB_TMO])) break; if (_sp > XB_SPIN_CAP) { atomicAdd(&(bar)[XB_TMO], 1u); break; } } } } while (0)
; __device__ __forceinline__ void xcd_barrier(const XcdBarrier& b) {
;     ...
;         const unsigned old = xb_add(&bar[XB_XSUB(b.x)], 1u);
;         const unsigned gen = old / nloc;
;         if (old + 1u == (gen + 1u) * nloc) {
;             __builtin_amdgcn_fence(__ATOMIC_RELEASE, "agent");
;             asm volatile("s_waitcnt vmcnt(0)" ::: "memory");
;             const unsigned og = xb_add(&bar[XB_TOP], 1u);
;             const unsigned tg = og / nx;
;             if (og + 1u == (tg + 1u) * nx) xb_add(&bar[XB_TOPGEN], 1u);
;             else XB_SPIN(xb_ld(&bar[XB_TOPGEN]) == tg, bar);
;             __builtin_amdgcn_fence(__ATOMIC_ACQUIRE, "agent");
;             xb_add(&bar[XB_XGEN(b.x)], 1u);
;             asm volatile("s_waitcnt vmcnt(0)" ::: "memory");
;         } else {
;             XB_SPIN(xb_ld(&bar[XB_XGEN(b.x)]) == gen, bar);
.LBB0_2040:
	v_readlane_b32 s4, v240, 25
	s_lshl_b32 s4, s4, 8
	v_readlane_b32 s10, v240, 23
	v_readlane_b32 s11, v240, 24
	s_add_u32 s4, s10, s4
	s_addc_u32 s5, s11, 0
	v_mov_b32_e32 v1, 0x1000
	v_mov_b32_e32 v3, 1
	global_atomic_add v3, v1, v3, s[4:5] offset:1024 sc0
	v_cvt_f32_u32_e32 v1, v2
	v_sub_u32_e32 v4, 0, v2
	v_rcp_iflag_f32_e32 v1, v1
	s_nop 0
	v_mul_f32_e32 v1, 0x4f7ffffe, v1
	v_cvt_u32_f32_e32 v1, v1
	v_mul_lo_u32 v4, v4, v1
	v_mul_hi_u32 v4, v1, v4
	v_add_u32_e32 v1, v1, v4
	s_waitcnt vmcnt(0)
	v_mul_hi_u32 v1, v3, v1
	v_mul_lo_u32 v4, v1, v2
	v_sub_u32_e32 v4, v3, v4
	v_add_u32_e32 v5, 1, v1
	v_cmp_ge_u32_e32 vcc, v4, v2
	v_add_u32_e32 v3, 1, v3
	s_nop 0
	v_cndmask_b32_e32 v1, v1, v5, vcc
	v_sub_u32_e32 v5, v4, v2
	v_cndmask_b32_e32 v4, v4, v5, vcc
	v_add_u32_e32 v5, 1, v1
	v_cmp_ge_u32_e32 vcc, v4, v2
	s_nop 1
	v_cndmask_b32_e32 v1, v1, v5, vcc
	v_mul_lo_u32 v4, v2, v1
	v_add_u32_e32 v2, v4, v2
	v_cmp_ne_u32_e32 vcc, v3, v2
	s_and_saveexec_b64 s[10:11], vcc
	s_xor_b64 s[10:11], exec, s[10:11]
	s_cbranch_execz .LBB0_2054
	s_waitcnt lgkmcnt(0)
	v_mov_b32_e32 v0, 0x7100
	global_load_dword v0, v0, s[30:31] offset:1024 sc1
	s_add_u32 s18, s30, 0x7500
	s_addc_u32 s19, s31, 0
	s_waitcnt vmcnt(0)
	v_cmp_eq_u32_e32 vcc, v0, v1
	s_and_saveexec_b64 s[12:13], vcc
	s_cbranch_execz .LBB0_2053
	s_add_u32 s16, s30, 0x4200
	s_addc_u32 s17, s31, 0
	s_mov_b32 s33, 1
	s_mov_b64 s[20:21], 0
	v_mov_b32_e32 v0, 0
	s_branch .LBB0_2044
